# gMLP unit loop software-pipelined: next unit's u/gate/v/LN-sum loads issued after the LN staging into spare registers, copied at the next loop top
# speedup vs baseline: 1.0063x; 1.0063x over previous
; #define LAS __attribute__((address_space(3)))
; __device__ __forceinline__ unsigned pk2(float lo, float hi) { f32x2_t v = {lo, hi}; bf16x2_t b = __builtin_convertvector(v, bf16x2_t); return __builtin_bit_cast(unsigned, b); }
; __device__ __forceinline__ void gmlp_stage_w(LAS unsigned char* lds, int g, const float* ws) {
;     int tid_l = threadIdx.x; asm volatile("" : "+v"(tid_l));
;     const int tid = tid_l; LAS bf16* Wa = (LAS bf16*)(lds + G_WA);
;     const int t = tid >> 2, sq = (tid & 3) * 32;
;     const float* wrow = ws + ((size_t)g * 128 + t) * 128 + sq;
; #pragma unroll
;     for (int j = 0; j < 8; ++j) {
;         const f32x4 v = *(const f32x4*)(wrow + 4 * j); const int s = sq + 4 * j;
;         const float a0 = (s + 0 <= t) ? v[0] : 0.f, a1 = (s + 1 <= t) ? v[1] : 0.f, a2 = (s + 2 <= t) ? v[2] : 0.f, a3 = (s + 3 <= t) ? v[3] : 0.f;
;         *(LAS v2u*)(Wa + t * 136 + s) = (v2u){pk2(a0, a1), pk2(a2, a3)};
;     }
; }
; __global__ void __launch_bounds__(NTHREADS, 2) fwd_megakernel(Args A) {
;     ...
;                 __syncthreads();
;                 if ((G & 7) == 0 && bx < 1024) gmlp_stage_w(lds, bx & 7, A.c_ws);
.LBB0_759:
	s_or_b64 exec, exec, s[0:1]
	s_mov_b32 s101, 1
	v_readlane_b32 s0, v253, 8
	v_readlane_b32 s1, v253, 9
	s_and_b64 vcc, exec, s[0:1]
	s_waitcnt lgkmcnt(0)
	s_barrier
	s_barrier
	s_cbranch_vccz .LBB0_761
	v_mov_b32_e32 v1, v145
	v_readlane_b32 s0, v254, 46
	s_waitcnt vmcnt(2)
	v_ashrrev_i32_e32 v14, 2, v1
	v_ashrrev_i32_e32 v15, 31, v14
	v_readlane_b32 s1, v254, 47
	v_lshlrev_b32_e32 v1, 5, v1
	v_and_b32_e32 v1, 0x60, v1
	v_lshl_add_u64 v[2:3], v[14:15], 0, s[0:1]
	v_readlane_b32 s0, v251, 5
	v_lshlrev_b64 v[2:3], 9, v[2:3]
	v_readlane_b32 s10, v251, 15
	v_readlane_b32 s11, v251, 16
	v_lshlrev_b32_e32 v4, 2, v1
	v_mov_b32_e32 v5, v0
	v_lshl_add_u64 v[2:3], s[10:11], 0, v[2:3]
	v_lshl_add_u64 v[16:17], v[2:3], 0, v[4:5]
	global_load_dwordx4 v[2:5], v[16:17], off offset:48
	global_load_dwordx4 v[6:9], v[16:17], off offset:32
	global_load_dwordx4 v[10:13], v[16:17], off offset:16
	global_load_dwordx4 v[18:21], v[16:17], off
	v_cmp_le_i32_e32 vcc, v1, v14
	v_or_b32_e32 v22, 2, v1
	s_movk_i32 s0, 0x110
	v_mul_lo_u32 v15, v14, s0
	v_readlane_b32 s1, v251, 6
	v_readlane_b32 s2, v251, 7
	v_readlane_b32 s3, v251, 8
	v_readlane_b32 s4, v251, 9
	v_readlane_b32 s5, v251, 10
	v_readlane_b32 s6, v251, 11
	v_readlane_b32 s7, v251, 12
	v_readlane_b32 s8, v251, 13
	v_readlane_b32 s9, v251, 14
	v_readlane_b32 s12, v251, 17
	v_readlane_b32 s13, v251, 18
	v_readlane_b32 s14, v251, 19
	v_readlane_b32 s15, v251, 20
	s_waitcnt vmcnt(0)
	v_cndmask_b32_e32 v18, 0, v18, vcc
	v_cmp_lt_i32_e32 vcc, v1, v14
	s_nop 1
	v_cndmask_b32_e32 v19, 0, v19, vcc
	v_cmp_le_i32_e32 vcc, v22, v14
	v_or_b32_e32 v22, 3, v1
	v_cvt_pk_bf16_f32 v18, v18, v19
	v_cndmask_b32_e32 v20, 0, v20, vcc
	v_cmp_le_i32_e32 vcc, v22, v14
	s_nop 1
	v_cndmask_b32_e32 v21, 0, v21, vcc
	v_cvt_pk_bf16_f32 v19, v20, v21
	v_lshlrev_b32_e32 v20, 1, v1
	v_add3_u32 v15, 0, v15, v20
	v_or_b32_e32 v20, 4, v1
	v_cmp_le_i32_e32 vcc, v20, v14
	s_nop 1
	v_cndmask_b32_e32 v10, 0, v10, vcc
	v_cmp_lt_i32_e32 vcc, v20, v14
	v_or_b32_e32 v20, 6, v1
	s_nop 0
	v_cndmask_b32_e32 v11, 0, v11, vcc
	v_cmp_le_i32_e32 vcc, v20, v14
	v_or_b32_e32 v20, 7, v1
	s_nop 0
	v_cndmask_b32_e32 v12, 0, v12, vcc
	v_cmp_le_i32_e32 vcc, v20, v14
	v_cvt_pk_bf16_f32 v20, v10, v11
	v_or_b32_e32 v10, 8, v1
	v_cndmask_b32_e32 v13, 0, v13, vcc
	v_cmp_le_i32_e32 vcc, v10, v14
	v_cvt_pk_bf16_f32 v21, v12, v13
	ds_write_b128 v15, v[18:21]
	v_cndmask_b32_e32 v6, 0, v6, vcc
	v_cmp_lt_i32_e32 vcc, v10, v14
	v_or_b32_e32 v10, 10, v1
	v_or_b32_e32 v20, 16, v1
	v_cndmask_b32_e32 v7, 0, v7, vcc
	v_cmp_le_i32_e32 vcc, v10, v14
	v_or_b32_e32 v10, 11, v1
	v_cvt_pk_bf16_f32 v6, v6, v7
	v_cndmask_b32_e32 v8, 0, v8, vcc
	v_cmp_le_i32_e32 vcc, v10, v14
	s_nop 1
	v_cndmask_b32_e32 v9, 0, v9, vcc
	v_cvt_pk_bf16_f32 v7, v8, v9
	v_or_b32_e32 v8, 12, v1
	v_cmp_le_i32_e32 vcc, v8, v14
	s_nop 1
	v_cndmask_b32_e32 v2, 0, v2, vcc
	v_cmp_lt_i32_e32 vcc, v8, v14
	v_or_b32_e32 v8, 14, v1
	s_nop 0
	v_cndmask_b32_e32 v3, 0, v3, vcc
	v_cmp_le_i32_e32 vcc, v8, v14
	v_or_b32_e32 v8, 15, v1
	s_nop 0
	v_cndmask_b32_e32 v4, 0, v4, vcc
	v_cmp_le_i32_e32 vcc, v8, v14
	v_cvt_pk_bf16_f32 v8, v2, v3
	s_nop 0
	v_cndmask_b32_e32 v5, 0, v5, vcc
	v_cvt_pk_bf16_f32 v9, v4, v5
	ds_write_b128 v15, v[6:9] offset:16
	global_load_dwordx4 v[2:5], v[16:17], off offset:112
	global_load_dwordx4 v[6:9], v[16:17], off offset:96
	global_load_dwordx4 v[10:13], v[16:17], off offset:80
	s_nop 0
	global_load_dwordx4 v[16:19], v[16:17], off offset:64
	v_cmp_le_i32_e32 vcc, v20, v14
	s_waitcnt vmcnt(0)
	s_nop 0
	v_cndmask_b32_e32 v16, 0, v16, vcc
	v_cmp_lt_i32_e32 vcc, v20, v14
	v_or_b32_e32 v20, 18, v1
	s_nop 0
	v_cndmask_b32_e32 v17, 0, v17, vcc
	v_cmp_le_i32_e32 vcc, v20, v14
	v_or_b32_e32 v20, 19, v1
	v_cvt_pk_bf16_f32 v16, v16, v17
	v_cndmask_b32_e32 v18, 0, v18, vcc
	v_cmp_le_i32_e32 vcc, v20, v14
	s_nop 1
	v_cndmask_b32_e32 v19, 0, v19, vcc
	v_cvt_pk_bf16_f32 v17, v18, v19
	v_or_b32_e32 v18, 20, v1
	v_cmp_le_i32_e32 vcc, v18, v14
	s_nop 1
	v_cndmask_b32_e32 v10, 0, v10, vcc
	v_cmp_lt_i32_e32 vcc, v18, v14
	v_or_b32_e32 v18, 22, v1
	s_nop 0
	v_cndmask_b32_e32 v11, 0, v11, vcc
	v_cmp_le_i32_e32 vcc, v18, v14
	v_or_b32_e32 v18, 23, v1
	s_nop 0
	v_cndmask_b32_e32 v12, 0, v12, vcc
	v_cmp_le_i32_e32 vcc, v18, v14
	v_cvt_pk_bf16_f32 v18, v10, v11
	v_or_b32_e32 v10, 24, v1
	v_cndmask_b32_e32 v13, 0, v13, vcc
	v_cmp_le_i32_e32 vcc, v10, v14
	v_cvt_pk_bf16_f32 v19, v12, v13
	ds_write_b128 v15, v[16:19] offset:32
	v_cndmask_b32_e32 v6, 0, v6, vcc
	v_cmp_lt_i32_e32 vcc, v10, v14
	v_or_b32_e32 v10, 26, v1
	s_nop 0
	v_cndmask_b32_e32 v7, 0, v7, vcc
	v_cmp_le_i32_e32 vcc, v10, v14
	v_or_b32_e32 v10, 27, v1
	v_cvt_pk_bf16_f32 v6, v6, v7
	v_cndmask_b32_e32 v8, 0, v8, vcc
	v_cmp_le_i32_e32 vcc, v10, v14
	s_nop 1
	v_cndmask_b32_e32 v9, 0, v9, vcc
	v_cvt_pk_bf16_f32 v7, v8, v9
	v_or_b32_e32 v8, 28, v1
	v_cmp_le_i32_e32 vcc, v8, v14
	s_nop 1
	v_cndmask_b32_e32 v2, 0, v2, vcc
	v_cmp_lt_i32_e32 vcc, v8, v14
	v_or_b32_e32 v8, 30, v1
	v_or_b32_e32 v1, 31, v1
	v_cndmask_b32_e32 v3, 0, v3, vcc
	v_cmp_le_i32_e32 vcc, v8, v14
	v_cvt_pk_bf16_f32 v8, v2, v3
	s_nop 0
	v_cndmask_b32_e32 v4, 0, v4, vcc
	v_cmp_le_i32_e32 vcc, v1, v14
	s_nop 1
	v_cndmask_b32_e32 v1, 0, v5, vcc
	v_cvt_pk_bf16_f32 v9, v4, v1
	ds_write_b128 v15, v[6:9] offset:48

; __device__ __forceinline__ void gmlp_unit(LAS unsigned char* lds, int unit, const bf16* U, const bf16* Vb, bf16* Y, const float* vs1, const float* vs2,
;                                           const float* lnw, const float* lnb, const float* bs) {
;     ...
;     const int t = 16 * w + l16;
;     v4u uu[4], gg[4];
; #pragma unroll
;     for (int j = 0; j < 4; ++j) { const size_t off = (m0 + t) * 1024 + c0 + 32 * j + 8 * g4; uu[j] = *(const v4u*)(U + off); gg[j] = *(const v4u*)(Y + off); }
;     {
;         const int s = tid >> 2, cq = (tid & 3) * 32;
;         const size_t row = m0 + s;
;         const float mean = vs1[row] * (1.f / 1024.f); const float var = vs2[row] * (1.f / 1024.f) - mean * mean; const float rstd = rsqrtf(fmaxf(var, 0.f) + EPS);
; #pragma unroll
;         for (int j = 0; j < 4; ++j) {
;             const int cc = cq + 8 * j;
;             const v4u vr = *(const v4u*)(Vb + row * 1024 + c0 + cc);
;             const f32x4 w0 = *(const f32x4*)(lnw + c0 + cc), w1 = *(const f32x4*)(lnw + c0 + cc + 4), b0 = *(const f32x4*)(lnb + c0 + cc), b1 = *(const f32x4*)(lnb + c0 + cc + 4);
.LBB0_765:
	v_mov_b32_e32 v1, v145
	s_ashr_i32 s0, s7, 3
	v_readfirstlane_b32 s2, v1
	s_ashr_i32 s2, s2, 2
	s_ashr_i32 s1, s0, 31
	v_bfi_b32 v84, -16, s2, v1
	s_lshl_b64 s[0:1], s[0:1], 7
	v_ashrrev_i32_e32 v85, 31, v84
	v_lshl_add_u64 v[82:83], s[0:1], 0, v[84:85]
	v_ashrrev_i32_e32 v34, 2, v1
	v_lshlrev_b32_e32 v35, 5, v1
	v_bfe_u32 v88, v1, 4, 2
	v_and_b32_e32 v90, 0x60, v35
	v_readlane_b32 s36, v251, 5
	s_lshl_b64 s[2:3], s[26:27], 2
	v_readlane_b32 s42, v251, 11
	v_readlane_b32 s43, v251, 12
	v_readlane_b32 s44, v251, 13
	v_readlane_b32 s45, v251, 14
	v_lshlrev_b32_e32 v89, 2, v90
	v_readlane_b32 s48, v251, 17
	v_readlane_b32 s49, v251, 18
	v_readlane_b32 s50, v251, 19
	v_readlane_b32 s51, v251, 20
	v_readlane_b32 s50, v255, 24
	v_readlane_b32 s51, v255, 25
	v_readlane_b32 s37, v251, 6
	v_readlane_b32 s38, v251, 7
	v_readlane_b32 s39, v251, 8
	v_readlane_b32 s40, v251, 9
	v_readlane_b32 s41, v251, 10
	v_readlane_b32 s46, v251, 15
	v_readlane_b32 s47, v251, 16
	v_lshlrev_b32_e32 v235, 1, v34
	s_cmp_eq_u32 s101, 0
	s_cbranch_scc1 .Lg3_nf
	s_mov_b32 s100, s7
	s_ashr_i32 s4, s100, 3
	s_ashr_i32 s5, s4, 31
	s_lshl_b64 s[4:5], s[4:5], 7
	s_and_b32 s100, s100, 7
	s_lshl_b32 s100, s100, 7
	v_mov_b32_e32 v36, v84
	v_mov_b32_e32 v37, 0
	v_lshl_add_u64 v[36:37], s[4:5], 0, v[36:37]
	v_lshlrev_b64 v[36:37], 10, v[36:37]
	v_or_b32_e32 v36, s100, v36
	v_or_b32_e32 v37, s27, v37
	v_lshl_or_b32 v36, v88, 3, v36
	v_lshlrev_b64 v[36:37], 1, v[36:37]
	v_lshl_add_u64 v[38:39], s[34:35], 0, v[36:37]
	v_lshl_add_u64 v[40:41], s[50:51], 0, v[36:37]
	global_load_dwordx4 v[92:95], v[38:39], off
	global_load_dwordx4 v[96:99], v[38:39], off offset:64
	global_load_dwordx4 v[100:103], v[38:39], off offset:128
	global_load_dwordx4 v[104:107], v[38:39], off offset:192
	global_load_dwordx4 v[108:111], v[40:41], off
	global_load_dwordx4 v[112:115], v[40:41], off offset:64
	global_load_dwordx4 v[116:119], v[40:41], off offset:128
	global_load_dwordx4 v[120:123], v[40:41], off offset:192
	v_ashrrev_i32_e32 v42, 2, v145
	v_ashrrev_i32_e32 v43, 31, v42
	v_lshl_add_u64 v[42:43], s[4:5], 0, v[42:43]
	v_lshlrev_b64 v[44:45], 2, v[42:43]
	v_readlane_b32 s4, v251, 21
	v_readlane_b32 s5, v251, 22
	s_nop 1
	v_lshl_add_u64 v[46:47], s[4:5], 0, v[44:45]
	global_load_dword v244, v[46:47], off
	v_readlane_b32 s4, v251, 23
	v_readlane_b32 s5, v251, 24
	s_nop 1
	v_lshl_add_u64 v[46:47], s[4:5], 0, v[44:45]
	global_load_dword v245, v[46:47], off
	v_lshlrev_b64 v[42:43], 11, v[42:43]
	v_readlane_b32 s4, v253, 0
	v_readlane_b32 s5, v253, 1
	s_nop 1
	v_lshl_add_u64 v[42:43], s[4:5], 0, v[42:43]
	s_lshl_b32 s4, s100, 1
	s_mov_b32 s5, 0
	v_lshl_add_u64 v[42:43], v[42:43], 0, s[4:5]
	v_and_b32_e32 v48, 3, v145
	v_lshlrev_b32_e32 v48, 6, v48
	v_mov_b32_e32 v49, 0
	v_lshl_add_u64 v[42:43], v[42:43], 0, v[48:49]
	global_load_dwordx4 v[124:127], v[42:43], off offset:48
	global_load_dwordx4 v[128:131], v[42:43], off offset:32
	global_load_dwordx4 v[132:135], v[42:43], off offset:16
	global_load_dwordx4 v[246:249], v[42:43], off
	s_mov_b32 s101, 0
.Lg3_nf:
	s_add_u32 s4, s42, s2
	s_addc_u32 s5, s43, s3
	s_add_u32 s2, s44, s2
	s_addc_u32 s3, s45, s3
	global_load_dwordx4 v[46:49], v89, s[4:5] offset:48
	global_load_dwordx4 v[58:61], v89, s[4:5] offset:32
	global_load_dwordx4 v[66:69], v89, s[4:5] offset:16
	global_load_dwordx4 v[74:77], v89, s[4:5]
	global_load_dwordx4 v[50:53], v89, s[2:3] offset:48
	global_load_dwordx4 v[62:65], v89, s[2:3] offset:32
	global_load_dwordx4 v[70:73], v89, s[2:3] offset:16
	global_load_dwordx4 v[78:81], v89, s[2:3]
	global_load_dwordx4 v[200:203], v89, s[4:5] offset:112
	global_load_dwordx4 v[204:207], v89, s[4:5] offset:96
	global_load_dwordx4 v[208:211], v89, s[4:5] offset:80
	global_load_dwordx4 v[224:227], v89, s[4:5] offset:64
	global_load_dwordx4 v[212:215], v89, s[2:3] offset:112
	global_load_dwordx4 v[216:219], v89, s[2:3] offset:96
	global_load_dwordx4 v[220:223], v89, s[2:3] offset:80
	global_load_dwordx4 v[228:231], v89, s[2:3] offset:64
	v_add_u32_e32 v198, s26, v84
	v_ashrrev_i32_e32 v199, 31, v198
	v_lshl_add_u64 v[198:199], v[198:199], 2, s[48:49]
	global_load_dword v232, v[198:199], off
	s_waitcnt vmcnt(17)
	v_mov_b32_e32 v30, v92
	v_mov_b32_e32 v31, v93
	v_mov_b32_e32 v32, v94
	v_mov_b32_e32 v33, v95
	v_mov_b32_e32 v22, v96
	v_mov_b32_e32 v23, v97
	v_mov_b32_e32 v24, v98
	v_mov_b32_e32 v25, v99
	v_mov_b32_e32 v14, v100
	v_mov_b32_e32 v15, v101
	v_mov_b32_e32 v16, v102
	v_mov_b32_e32 v17, v103
	v_mov_b32_e32 v6, v104
	v_mov_b32_e32 v7, v105
	v_mov_b32_e32 v8, v106
	v_mov_b32_e32 v9, v107
	v_mov_b32_e32 v26, v108
	v_mov_b32_e32 v27, v109
	v_mov_b32_e32 v28, v110
	v_mov_b32_e32 v29, v111
	v_mov_b32_e32 v18, v112
	v_mov_b32_e32 v19, v113
	v_mov_b32_e32 v20, v114
	v_mov_b32_e32 v21, v115
	v_mov_b32_e32 v10, v116
	v_mov_b32_e32 v11, v117
	v_mov_b32_e32 v12, v118
	v_mov_b32_e32 v13, v119
	v_mov_b32_e32 v2, v120
	v_mov_b32_e32 v3, v121
	v_mov_b32_e32 v4, v122
	v_mov_b32_e32 v5, v123
	v_mov_b32_e32 v34, v124
	v_mov_b32_e32 v35, v125
	v_mov_b32_e32 v36, v126
	v_mov_b32_e32 v37, v127
	v_mov_b32_e32 v38, v128
	v_mov_b32_e32 v39, v129
	v_mov_b32_e32 v40, v130
	v_mov_b32_e32 v41, v131
	v_mov_b32_e32 v42, v132
	v_mov_b32_e32 v43, v133
	v_mov_b32_e32 v44, v134
	v_mov_b32_e32 v45, v135
	v_mov_b32_e32 v54, v246
	v_mov_b32_e32 v55, v247
	v_mov_b32_e32 v56, v248
	v_mov_b32_e32 v57, v249
	v_mov_b32_e32 v197, v244
	v_mov_b32_e32 v196, v245
	v_mul_u32_u24_e32 v90, 0x110, v90
	s_add_i32 s7, s7, s84
	s_lshl_b64 s[0:1], s[26:27], 1
	s_waitcnt vmcnt(0)
; #define LAS __attribute__((address_space(3)))
; __device__ __forceinline__ float bflo(unsigned u) { return __uint_as_float(u << 16); }
; __device__ __forceinline__ float bfhi(unsigned u) { return __uint_as_float(u & 0xffff0000u); }
; __device__ __forceinline__ unsigned short f2bf(float f) { return (unsigned short)(pk2(f, 0.f) & 0xffffu); }
; __device__ __forceinline__ void gmlp_unit(LAS unsigned char* lds, int unit, const bf16* U, const bf16* Vb, bf16* Y, const float* vs1, const float* vs2,
;                                           const float* lnw, const float* lnb, const float* bs) {
;     ...
;         const float mean = vs1[row] * (1.f / 1024.f); const float var = vs2[row] * (1.f / 1024.f) - mean * mean; const float rstd = rsqrtf(fmaxf(var, 0.f) + EPS);
; #pragma unroll
;         for (int j = 0; j < 4; ++j) {
;             const int cc = cq + 8 * j;
;             const v4u vr = *(const v4u*)(Vb + row * 1024 + c0 + cc);
;             const f32x4 w0 = *(const f32x4*)(lnw + c0 + cc), w1 = *(const f32x4*)(lnw + c0 + cc + 4), b0 = *(const f32x4*)(lnb + c0 + cc), b1 = *(const f32x4*)(lnb + c0 + cc + 4);
;             LAS bf16* vd = Vt + cc * 136 + s;
;             vd[0 * 136] = f2bf((bflo(vr.x) - mean) * rstd * w0[0] + b0[0]); vd[1 * 136] = f2bf((bfhi(vr.x) - mean) * rstd * w0[1] + b0[1]);
;             vd[2 * 136] = f2bf((bflo(vr.y) - mean) * rstd * w0[2] + b0[2]); vd[3 * 136] = f2bf((bfhi(vr.y) - mean) * rstd * w0[3] + b0[3]);
;             vd[4 * 136] = f2bf((bflo(vr.z) - mean) * rstd * w1[0] + b1[0]); vd[5 * 136] = f2bf((bfhi(vr.z) - mean) * rstd * w1[1] + b1[1]);
;             vd[6 * 136] = f2bf((bflo(vr.w) - mean) * rstd * w1[2] + b1[2]); vd[7 * 136] = f2bf((bfhi(vr.w) - mean) * rstd * w1[3] + b1[3]);
	v_mul_f32_e32 v86, 0x3a800000, v196
	v_mul_f32_e32 v87, 0x3a800000, v197
	v_fma_f32 v233, -v87, v87, v86
	v_max_f32_e32 v233, 0, v233
	v_add_f32_e32 v233, 0x358637bd, v233
	v_rsq_f32_e32 v85, v233
	s_nop 0
	v_add3_u32 v86, 0, v235, v90
	v_lshlrev_b32_e32 v90, 16, v54
	v_and_b32_e32 v54, 0xffff0000, v54
	v_sub_f32_e32 v54, v54, v87
	v_mul_f32_e32 v54, v54, v85
	v_fma_f32 v54, v75, v54, v79
	v_cvt_pk_bf16_f32 v54, v54, s0
	ds_write_b16 v86, v54 offset:35088
	v_lshlrev_b32_e32 v54, 16, v55
	v_sub_f32_e32 v54, v54, v87
	v_mul_f32_e32 v54, v54, v85
	v_fma_f32 v54, v76, v54, v80
	v_cvt_pk_bf16_f32 v54, v54, s0
	ds_write_b16 v86, v54 offset:35360
	v_and_b32_e32 v54, 0xffff0000, v55
	v_sub_f32_e32 v54, v54, v87
	v_mul_f32_e32 v54, v54, v85
	v_fmac_f32_e32 v81, v77, v54
	v_cvt_pk_bf16_f32 v54, v81, s0
	ds_write_b16 v86, v54 offset:35632
	v_lshlrev_b32_e32 v54, 16, v56
	v_sub_f32_e32 v54, v54, v87
	v_mul_f32_e32 v54, v54, v85
	v_fma_f32 v54, v66, v54, v70
	v_cvt_pk_bf16_f32 v54, v54, s0
	ds_write_b16 v86, v54 offset:35904
	v_and_b32_e32 v54, 0xffff0000, v56
	v_sub_f32_e32 v54, v54, v87
	v_mul_f32_e32 v54, v54, v85
	v_fma_f32 v54, v67, v54, v71
	v_cvt_pk_bf16_f32 v54, v54, s0
	ds_write_b16 v86, v54 offset:36176
	v_lshlrev_b32_e32 v54, 16, v57
	v_sub_f32_e32 v54, v54, v87
	v_mul_f32_e32 v54, v54, v85
	v_fma_f32 v54, v68, v54, v72
	v_cvt_pk_bf16_f32 v54, v54, s0
	ds_write_b16 v86, v54 offset:36448
	v_and_b32_e32 v54, 0xffff0000, v57
	v_sub_f32_e32 v54, v54, v87
	v_mul_f32_e32 v54, v54, v85
	v_fmac_f32_e32 v73, v69, v54
	v_cvt_pk_bf16_f32 v54, v73, s0
	ds_write_b16 v86, v54 offset:36720
	v_lshlrev_b32_e32 v54, 16, v42
	v_and_b32_e32 v42, 0xffff0000, v42
	v_sub_f32_e32 v42, v42, v87
	v_mul_f32_e32 v42, v85, v42
	v_fma_f32 v42, v59, v42, v63
	v_cvt_pk_bf16_f32 v42, v42, s0
	ds_write_b16 v86, v42 offset:37264
	v_lshlrev_b32_e32 v42, 16, v43
	v_sub_f32_e32 v42, v42, v87
	v_mul_f32_e32 v42, v85, v42
	v_fma_f32 v42, v60, v42, v64
	v_cvt_pk_bf16_f32 v42, v42, s0
	ds_write_b16 v86, v42 offset:37536
	v_and_b32_e32 v42, 0xffff0000, v43
	v_sub_f32_e32 v42, v42, v87
	v_mul_f32_e32 v42, v85, v42
	v_fmac_f32_e32 v65, v61, v42
	v_cvt_pk_bf16_f32 v42, v65, s0
	ds_write_b16 v86, v42 offset:37808
	v_lshlrev_b32_e32 v42, 16, v44
	v_sub_f32_e32 v42, v42, v87
	v_mul_f32_e32 v42, v85, v42
	v_fma_f32 v42, v46, v42, v50
	v_cvt_pk_bf16_f32 v42, v42, s0
	ds_write_b16 v86, v42 offset:38080
	v_and_b32_e32 v42, 0xffff0000, v44
	v_sub_f32_e32 v42, v42, v87
	v_mul_f32_e32 v42, v85, v42
	v_fma_f32 v42, v47, v42, v51
	v_cvt_pk_bf16_f32 v42, v42, s0
	ds_write_b16 v86, v42 offset:38352
	v_lshlrev_b32_e32 v42, 16, v45
	v_sub_f32_e32 v42, v42, v87
	v_mul_f32_e32 v42, v85, v42
	v_fma_f32 v42, v48, v42, v52
	v_cvt_pk_bf16_f32 v42, v42, s0
	ds_write_b16 v86, v42 offset:38624
	v_and_b32_e32 v42, 0xffff0000, v45
	v_sub_f32_e32 v90, v90, v87
	v_sub_f32_e32 v54, v54, v87
	v_sub_f32_e32 v42, v42, v87
	v_mul_f32_e32 v90, v90, v85
	v_mul_f32_e32 v54, v85, v54
	v_mul_f32_e32 v42, v85, v42
	v_fma_f32 v74, v74, v90, v78
	v_fma_f32 v54, v58, v54, v62
	v_fmac_f32_e32 v53, v49, v42
	v_cvt_pk_bf16_f32 v74, v74, s0
	v_cvt_pk_bf16_f32 v54, v54, s0
	v_cvt_pk_bf16_f32 v42, v53, s0
	ds_write_b16 v86, v74 offset:34816
	ds_write_b16 v86, v54 offset:36992
	ds_write_b16 v86, v42 offset:38896
	v_lshlrev_b32_e32 v74, 16, v38
	v_and_b32_e32 v38, 0xffff0000, v38
	v_sub_f32_e32 v38, v38, v87
	v_mul_f32_e32 v38, v85, v38
	v_sub_f32_e32 v74, v74, v87
	v_mul_f32_e32 v74, v85, v74
	s_movk_i32 s2, 0x110
	v_fma_f32 v38, v225, v38, v229
	v_cvt_pk_bf16_f32 v38, v38, s0
	ds_write_b16 v86, v38 offset:39440
	v_lshlrev_b32_e32 v38, 16, v39
	v_sub_f32_e32 v38, v38, v87
	v_mul_f32_e32 v38, v85, v38
	v_fma_f32 v38, v226, v38, v230
	v_cvt_pk_bf16_f32 v38, v38, s0
	ds_write_b16 v86, v38 offset:39712
	v_and_b32_e32 v38, 0xffff0000, v39
	v_sub_f32_e32 v38, v38, v87
	v_mul_f32_e32 v38, v85, v38
	v_fmac_f32_e32 v231, v227, v38
	v_cvt_pk_bf16_f32 v38, v231, s0
	ds_write_b16 v86, v38 offset:39984
	v_lshlrev_b32_e32 v38, 16, v40
	v_sub_f32_e32 v38, v38, v87
	v_mul_f32_e32 v38, v85, v38
	v_fma_f32 v38, v208, v38, v220
	v_cvt_pk_bf16_f32 v38, v38, s0
	ds_write_b16 v86, v38 offset:40256
	v_and_b32_e32 v38, 0xffff0000, v40
	v_sub_f32_e32 v38, v38, v87
	v_mul_f32_e32 v38, v85, v38
	v_fma_f32 v38, v209, v38, v221
	v_cvt_pk_bf16_f32 v38, v38, s0
	ds_write_b16 v86, v38 offset:40528
	v_lshlrev_b32_e32 v38, 16, v41
	v_sub_f32_e32 v38, v38, v87
	v_mul_f32_e32 v38, v85, v38
	v_fma_f32 v38, v210, v38, v222
	v_cvt_pk_bf16_f32 v38, v38, s0
	ds_write_b16 v86, v38 offset:40800
	v_and_b32_e32 v38, 0xffff0000, v41
	v_sub_f32_e32 v38, v38, v87
	v_mul_f32_e32 v38, v85, v38
	v_fmac_f32_e32 v223, v211, v38
	v_cvt_pk_bf16_f32 v38, v223, s0
	ds_write_b16 v86, v38 offset:41072
	v_lshlrev_b32_e32 v38, 16, v34
	v_and_b32_e32 v34, 0xffff0000, v34
	v_sub_f32_e32 v34, v34, v87
	v_mul_f32_e32 v34, v85, v34
	v_fma_f32 v34, v205, v34, v217
	v_cvt_pk_bf16_f32 v34, v34, s0
	ds_write_b16 v86, v34 offset:41616
	v_lshlrev_b32_e32 v34, 16, v35
	v_sub_f32_e32 v34, v34, v87
	v_mul_f32_e32 v34, v85, v34
	v_fma_f32 v34, v206, v34, v218
	v_cvt_pk_bf16_f32 v34, v34, s0
	ds_write_b16 v86, v34 offset:41888
	v_and_b32_e32 v34, 0xffff0000, v35
	v_sub_f32_e32 v34, v34, v87
	v_mul_f32_e32 v34, v85, v34
	v_fmac_f32_e32 v219, v207, v34
	v_cvt_pk_bf16_f32 v34, v219, s0
	ds_write_b16 v86, v34 offset:42160
	v_lshlrev_b32_e32 v34, 16, v36
	v_sub_f32_e32 v34, v34, v87
	v_mul_f32_e32 v34, v85, v34
	v_fma_f32 v34, v200, v34, v212
	v_cvt_pk_bf16_f32 v34, v34, s0
	ds_write_b16 v86, v34 offset:42432
	v_and_b32_e32 v34, 0xffff0000, v36
	v_sub_f32_e32 v34, v34, v87
	v_mul_f32_e32 v34, v85, v34
; #define LAS __attribute__((address_space(3)))
; __device__ __forceinline__ float bflo(unsigned u) { return __uint_as_float(u << 16); }
; __device__ __forceinline__ float bfhi(unsigned u) { return __uint_as_float(u & 0xffff0000u); }
; __device__ __forceinline__ void gmlp_unit(LAS unsigned char* lds, int unit, const bf16* U, const bf16* Vb, bf16* Y, const float* vs1, const float* vs2,
;                                           const float* lnw, const float* lnb, const float* bs) {
;     ...
;     for (int j = 0; j < 4; ++j) { const size_t off = (m0 + t) * 1024 + c0 + 32 * j + 8 * g4; uu[j] = *(const v4u*)(U + off); gg[j] = *(const v4u*)(Y + off); }
;     {
;         const int s = tid >> 2, cq = (tid & 3) * 32;
;         const size_t row = m0 + s;
;         const float mean = vs1[row] * (1.f / 1024.f); const float var = vs2[row] * (1.f / 1024.f) - mean * mean; const float rstd = rsqrtf(fmaxf(var, 0.f) + EPS);
; #pragma unroll
;         for (int j = 0; j < 4; ++j) {
;             const int cc = cq + 8 * j;
;             const v4u vr = *(const v4u*)(Vb + row * 1024 + c0 + cc);
;     ...
;     LBAR();
;     bf16x8 bw[4];
; #pragma unroll
;     for (int ks = 0; ks < 4; ++ks) bw[ks] = *(const LAS bf16x8*)(Wa + (16 * w + l16) * 136 + 32 * ks + 8 * g4);
;     const float bias = bs[g * 128 + t];
; #pragma unroll
;     for (int j = 0; j < 4; ++j) {
;         const int crow = 32 * j + 8 * (l16 >> 2) + (l16 & 3);
;         f32x4 e4 = (f32x4){0.f, 0.f, 0.f, 0.f}, o4 = e4;
; #pragma unroll
;         for (int ks = 0; ks < 4; ++ks) {
;             const bf16x8 ae = *(const LAS bf16x8*)(Vt + crow * 136 + 32 * ks + 8 * g4), ao = *(const LAS bf16x8*)(Vt + (crow + 4) * 136 + 32 * ks + 8 * g4);
;             e4 = mfma16(ae, bw[ks], e4); o4 = mfma16(ao, bw[ks], o4);
;         }
;         const size_t off = (m0 + t) * 1024 + c0 + 32 * j + 8 * g4;
;         const v4u u4 = uu[j], g4v = gg[j];
;         v4u y;
;         y.x = pk2(bflo(u4.x) * (e4[0] + bias) * bflo(g4v.x), bfhi(u4.x) * (e4[1] + bias) * bfhi(g4v.x)); y.y = pk2(bflo(u4.y) * (e4[2] + bias) * bflo(g4v.y), bfhi(u4.y) * (e4[3] + bias) * bfhi(g4v.y));
;         y.z = pk2(bflo(u4.z) * (o4[0] + bias) * bflo(g4v.z), bfhi(u4.z) * (o4[1] + bias) * bfhi(g4v.z)); y.w = pk2(bflo(u4.w) * (o4[2] + bias) * bflo(g4v.w), bfhi(u4.w) * (o4[3] + bias) * bfhi(g4v.w));
;         *(v4u*)(Y + off) = y;
	v_fma_f32 v34, v201, v34, v213
	v_cvt_pk_bf16_f32 v34, v34, s0
	ds_write_b16 v86, v34 offset:42704
	v_lshlrev_b32_e32 v34, 16, v37
	v_sub_f32_e32 v34, v34, v87
	v_mul_f32_e32 v34, v85, v34
	v_fma_f32 v34, v202, v34, v214
	v_cvt_pk_bf16_f32 v34, v34, s0
	ds_write_b16 v86, v34 offset:42976
	v_and_b32_e32 v34, 0xffff0000, v37
	v_sub_f32_e32 v38, v38, v87
	v_sub_f32_e32 v34, v34, v87
	v_mul_f32_e32 v38, v85, v38
	v_mul_f32_e32 v34, v85, v34
	v_fma_f32 v224, v224, v74, v228
	v_fma_f32 v38, v204, v38, v216
	v_fmac_f32_e32 v215, v203, v34
	v_cvt_pk_bf16_f32 v224, v224, s0
	v_cvt_pk_bf16_f32 v38, v38, s0
	v_cvt_pk_bf16_f32 v34, v215, s0
	v_add_u32_e32 v50, s26, v84
	ds_write_b16 v86, v224 offset:39168
	ds_write_b16 v86, v38 offset:41344
	ds_write_b16 v86, v34 offset:43248
	s_sub_i32 s100, s7, s84
	s_cmpk_lt_i32 s7, 0x400
	s_cselect_b32 s100, s7, s100
	s_ashr_i32 s4, s100, 3
	s_ashr_i32 s5, s4, 31
	s_lshl_b64 s[4:5], s[4:5], 7
	s_and_b32 s100, s100, 7
	s_lshl_b32 s100, s100, 7
	v_mov_b32_e32 v36, v84
	v_mov_b32_e32 v37, 0
	v_lshl_add_u64 v[36:37], s[4:5], 0, v[36:37]
	v_lshlrev_b64 v[36:37], 10, v[36:37]
	v_or_b32_e32 v36, s100, v36
	v_or_b32_e32 v37, s27, v37
	v_lshl_or_b32 v36, v88, 3, v36
	v_lshlrev_b64 v[36:37], 1, v[36:37]
	v_lshl_add_u64 v[38:39], s[34:35], 0, v[36:37]
	v_lshl_add_u64 v[40:41], s[50:51], 0, v[36:37]
	global_load_dwordx4 v[92:95], v[38:39], off
	global_load_dwordx4 v[96:99], v[38:39], off offset:64
	global_load_dwordx4 v[100:103], v[38:39], off offset:128
	global_load_dwordx4 v[104:107], v[38:39], off offset:192
	global_load_dwordx4 v[108:111], v[40:41], off
	global_load_dwordx4 v[112:115], v[40:41], off offset:64
	global_load_dwordx4 v[116:119], v[40:41], off offset:128
	global_load_dwordx4 v[120:123], v[40:41], off offset:192
	v_ashrrev_i32_e32 v42, 2, v145
	v_ashrrev_i32_e32 v43, 31, v42
	v_lshl_add_u64 v[42:43], s[4:5], 0, v[42:43]
	v_lshlrev_b64 v[44:45], 2, v[42:43]
	v_readlane_b32 s4, v251, 21
	v_readlane_b32 s5, v251, 22
	s_nop 1
	v_lshl_add_u64 v[46:47], s[4:5], 0, v[44:45]
	global_load_dword v244, v[46:47], off
	v_readlane_b32 s4, v251, 23
	v_readlane_b32 s5, v251, 24
	s_nop 1
	v_lshl_add_u64 v[46:47], s[4:5], 0, v[44:45]
	global_load_dword v245, v[46:47], off
	v_lshlrev_b64 v[42:43], 11, v[42:43]
	v_readlane_b32 s4, v253, 0
	v_readlane_b32 s5, v253, 1
	s_nop 1
	v_lshl_add_u64 v[42:43], s[4:5], 0, v[42:43]
	s_lshl_b32 s4, s100, 1
	s_mov_b32 s5, 0
	v_lshl_add_u64 v[42:43], v[42:43], 0, s[4:5]
	v_and_b32_e32 v48, 3, v145
	v_lshlrev_b32_e32 v48, 6, v48
	v_mov_b32_e32 v49, 0
	v_lshl_add_u64 v[42:43], v[42:43], 0, v[48:49]
	global_load_dwordx4 v[124:127], v[42:43], off offset:48
	global_load_dwordx4 v[128:131], v[42:43], off offset:32
	global_load_dwordx4 v[132:135], v[42:43], off offset:16
	global_load_dwordx4 v[246:249], v[42:43], off
	v_mul_lo_u32 v34, v84, s2
	v_lshlrev_b32_e32 v54, 4, v88
	v_ashrrev_i32_e32 v51, 31, v50
	s_waitcnt lgkmcnt(0)
	s_barrier
	v_add3_u32 v34, 0, v34, v54
	v_lshl_add_u64 v[50:51], v[50:51], 2, s[48:49]
	ds_read_b128 v[46:49], v34
	ds_read_b128 v[42:45], v34 offset:64
	ds_read_b128 v[38:41], v34 offset:128
	ds_read_b128 v[34:37], v34 offset:192
	v_mov_b32_e32 v50, v232
	v_lshlrev_b32_e32 v51, 1, v1
	v_and_b32_e32 v1, 3, v1
	v_and_or_b32 v1, v51, 24, v1
	v_lshlrev_b64 v[52:53], 11, v[82:83]
	v_lshl_add_u64 v[52:53], s[50:51], 0, v[52:53]
	v_mul_u32_u24_e32 v1, 0x110, v1
	v_lshl_add_u64 v[52:53], v[52:53], 0, s[0:1]
	v_mov_b32_e32 v55, v0
	v_add3_u32 v1, 0, v1, v54
	v_lshl_add_u64 v[52:53], v[52:53], 0, v[54:55]
	ds_read_b128 v[54:57], v1 offset:34816
	ds_read_b128 v[58:61], v1 offset:35904
	ds_read_b128 v[62:65], v1 offset:34880
	ds_read_b128 v[66:69], v1 offset:35968
	s_waitcnt lgkmcnt(3)
	v_mfma_f32_16x16x32_bf16 v[54:57], v[54:57], v[46:49], 0
	v_readlane_b32 s0, v254, 54
	s_add_i32 s6, s6, s0
	s_cmpk_gt_i32 s7, 0x3ff
	s_waitcnt lgkmcnt(2)
	v_mfma_f32_16x16x32_bf16 v[58:61], v[58:61], v[46:49], 0
	s_waitcnt lgkmcnt(1)
	v_mfma_f32_16x16x32_bf16 v[54:57], v[62:65], v[42:45], v[54:57]
	s_waitcnt lgkmcnt(0)
	v_mfma_f32_16x16x32_bf16 v[58:61], v[66:69], v[42:45], v[58:61]
	ds_read_b128 v[62:65], v1 offset:34944
	ds_read_b128 v[66:69], v1 offset:36032
	s_waitcnt lgkmcnt(1)
	v_mfma_f32_16x16x32_bf16 v[54:57], v[62:65], v[38:41], v[54:57]
	s_waitcnt lgkmcnt(0)
	v_mfma_f32_16x16x32_bf16 v[58:61], v[66:69], v[38:41], v[58:61]
	ds_read_b128 v[62:65], v1 offset:35008
	ds_read_b128 v[66:69], v1 offset:36096
	s_waitcnt lgkmcnt(1)
	v_mfma_f32_16x16x32_bf16 v[54:57], v[62:65], v[34:37], v[54:57]
	v_lshlrev_b32_e32 v62, 16, v30
	v_and_b32_e32 v63, 0xffff0000, v30
	v_lshlrev_b32_e32 v30, 16, v31
	s_waitcnt lgkmcnt(0)
	v_mfma_f32_16x16x32_bf16 v[58:61], v[66:69], v[34:37], v[58:61]
	v_and_b32_e32 v31, 0xffff0000, v31
	s_nop 0
	v_pk_add_f32 v[54:55], v[50:51], v[54:55] op_sel_hi:[0,1]
	v_pk_mul_f32 v[54:55], v[54:55], v[62:63]
	v_lshlrev_b32_e32 v62, 16, v26
	v_and_b32_e32 v63, 0xffff0000, v26
	v_pk_mul_f32 v[54:55], v[54:55], v[62:63]
	s_nop 0
	v_cvt_pk_bf16_f32 v26, v54, v55
	v_pk_add_f32 v[54:55], v[50:51], v[56:57] op_sel_hi:[0,1]
	v_pk_mul_f32 v[30:31], v[54:55], v[30:31]
	v_lshlrev_b32_e32 v54, 16, v27
	v_and_b32_e32 v55, 0xffff0000, v27
	v_pk_mul_f32 v[30:31], v[30:31], v[54:55]
	v_pk_add_f32 v[54:55], v[50:51], v[58:59] op_sel_hi:[0,1]
	v_cvt_pk_bf16_f32 v27, v30, v31
	v_lshlrev_b32_e32 v30, 16, v32
	v_and_b32_e32 v31, 0xffff0000, v32
	v_pk_mul_f32 v[30:31], v[54:55], v[30:31]
	v_lshlrev_b32_e32 v54, 16, v28
	v_and_b32_e32 v55, 0xffff0000, v28
	v_pk_mul_f32 v[30:31], v[30:31], v[54:55]
	s_nop 0
	v_cvt_pk_bf16_f32 v28, v30, v31
	v_lshlrev_b32_e32 v30, 16, v33
	v_and_b32_e32 v31, 0xffff0000, v33
	v_pk_add_f32 v[32:33], v[50:51], v[60:61] op_sel_hi:[0,1]
	v_pk_mul_f32 v[30:31], v[32:33], v[30:31]
	v_lshlrev_b32_e32 v32, 16, v29
	v_and_b32_e32 v33, 0xffff0000, v29
	v_pk_mul_f32 v[30:31], v[30:31], v[32:33]
	s_nop 0
	v_cvt_pk_bf16_f32 v29, v30, v31
	global_store_dwordx4 v[52:53], v[26:29], off
	ds_read_b128 v[26:29], v1 offset:43520
	ds_read_b128 v[30:33], v1 offset:44608
	ds_read_b128 v[54:57], v1 offset:43584
	ds_read_b128 v[58:61], v1 offset:44672
	s_waitcnt lgkmcnt(3)
; #define LAS __attribute__((address_space(3)))
; __device__ __forceinline__ float bflo(unsigned u) { return __uint_as_float(u << 16); }
; __device__ __forceinline__ float bfhi(unsigned u) { return __uint_as_float(u & 0xffff0000u); }
; __device__ __forceinline__ unsigned pk2(float lo, float hi) { f32x2_t v = {lo, hi}; bf16x2_t b = __builtin_convertvector(v, bf16x2_t); return __builtin_bit_cast(unsigned, b); }
; __device__ __forceinline__ f32x4 mfma16(bf16x8 a, bf16x8 b, f32x4 c) { return __builtin_amdgcn_mfma_f32_16x16x32_bf16(a, b, c, 0, 0, 0); }
; #define LBAR() do { asm volatile("s_waitcnt lgkmcnt(0)" ::: "memory"); __builtin_amdgcn_s_barrier(); asm volatile("" ::: "memory"); } while (0)
; __device__ __forceinline__ void gmlp_unit(LAS unsigned char* lds, int unit, const bf16* U, const bf16* Vb, bf16* Y, const float* vs1, const float* vs2,
;                                           const float* lnw, const float* lnb, const float* bs) {
;     ...
;     for (int j = 0; j < 4; ++j) {
;         const int crow = 32 * j + 8 * (l16 >> 2) + (l16 & 3);
;         f32x4 e4 = (f32x4){0.f, 0.f, 0.f, 0.f}, o4 = e4;
; #pragma unroll
;         for (int ks = 0; ks < 4; ++ks) {
;             const bf16x8 ae = *(const LAS bf16x8*)(Vt + crow * 136 + 32 * ks + 8 * g4), ao = *(const LAS bf16x8*)(Vt + (crow + 4) * 136 + 32 * ks + 8 * g4);
;             e4 = mfma16(ae, bw[ks], e4); o4 = mfma16(ao, bw[ks], o4);
;         }
;         const size_t off = (m0 + t) * 1024 + c0 + 32 * j + 8 * g4;
;         const v4u u4 = uu[j], g4v = gg[j];
;         v4u y;
;         y.x = pk2(bflo(u4.x) * (e4[0] + bias) * bflo(g4v.x), bfhi(u4.x) * (e4[1] + bias) * bfhi(g4v.x)); y.y = pk2(bflo(u4.y) * (e4[2] + bias) * bflo(g4v.y), bfhi(u4.y) * (e4[3] + bias) * bfhi(g4v.y));
;         y.z = pk2(bflo(u4.z) * (o4[0] + bias) * bflo(g4v.z), bfhi(u4.z) * (o4[1] + bias) * bfhi(g4v.z)); y.w = pk2(bflo(u4.w) * (o4[2] + bias) * bflo(g4v.w), bfhi(u4.w) * (o4[3] + bias) * bfhi(g4v.w));
;         *(v4u*)(Y + off) = y;
;     }
;     LBAR();
	v_mfma_f32_16x16x32_bf16 v[26:29], v[26:29], v[46:49], 0
	s_waitcnt lgkmcnt(2)
	v_mfma_f32_16x16x32_bf16 v[30:33], v[30:33], v[46:49], 0
	s_waitcnt lgkmcnt(1)
	v_mfma_f32_16x16x32_bf16 v[26:29], v[54:57], v[42:45], v[26:29]
	s_waitcnt lgkmcnt(0)
	v_mfma_f32_16x16x32_bf16 v[30:33], v[58:61], v[42:45], v[30:33]
	ds_read_b128 v[54:57], v1 offset:43648
	ds_read_b128 v[58:61], v1 offset:44736
	s_waitcnt lgkmcnt(1)
	v_mfma_f32_16x16x32_bf16 v[26:29], v[54:57], v[38:41], v[26:29]
	s_waitcnt lgkmcnt(0)
	v_mfma_f32_16x16x32_bf16 v[30:33], v[58:61], v[38:41], v[30:33]
	ds_read_b128 v[54:57], v1 offset:43712
	ds_read_b128 v[58:61], v1 offset:44800
	s_waitcnt lgkmcnt(1)
	v_mfma_f32_16x16x32_bf16 v[26:29], v[54:57], v[34:37], v[26:29]
	v_lshlrev_b32_e32 v54, 16, v22
	v_and_b32_e32 v55, 0xffff0000, v22
	v_lshlrev_b32_e32 v22, 16, v23
	s_waitcnt lgkmcnt(0)
	v_mfma_f32_16x16x32_bf16 v[30:33], v[58:61], v[34:37], v[30:33]
	s_nop 2
	v_add_f32_e64 v26, v50, v26
	v_add_f32_e64 v27, v50, v27
	v_pk_mul_f32 v[26:27], v[26:27], v[54:55]
	v_lshlrev_b32_e32 v54, 16, v18
	v_and_b32_e32 v55, 0xffff0000, v18
	v_pk_mul_f32 v[26:27], v[26:27], v[54:55]
	v_and_b32_e32 v23, 0xffff0000, v23
	v_cvt_pk_bf16_f32 v18, v26, v27
	v_pk_add_f32 v[26:27], v[50:51], v[28:29] op_sel_hi:[0,1]
	v_pk_mul_f32 v[22:23], v[26:27], v[22:23]
	v_lshlrev_b32_e32 v26, 16, v19
	v_and_b32_e32 v27, 0xffff0000, v19
	v_pk_mul_f32 v[22:23], v[22:23], v[26:27]
	v_pk_add_f32 v[26:27], v[50:51], v[30:31] op_sel_hi:[0,1]
	v_cvt_pk_bf16_f32 v19, v22, v23
	v_lshlrev_b32_e32 v22, 16, v24
	v_and_b32_e32 v23, 0xffff0000, v24
	v_pk_mul_f32 v[22:23], v[26:27], v[22:23]
	v_lshlrev_b32_e32 v26, 16, v20
	v_and_b32_e32 v27, 0xffff0000, v20
	v_pk_mul_f32 v[22:23], v[22:23], v[26:27]
	s_nop 0
	v_cvt_pk_bf16_f32 v20, v22, v23
	v_lshlrev_b32_e32 v22, 16, v25
	v_and_b32_e32 v23, 0xffff0000, v25
	v_pk_add_f32 v[24:25], v[50:51], v[32:33] op_sel_hi:[0,1]
	v_pk_mul_f32 v[22:23], v[24:25], v[22:23]
	v_lshlrev_b32_e32 v24, 16, v21
	v_and_b32_e32 v25, 0xffff0000, v21
	v_pk_mul_f32 v[22:23], v[22:23], v[24:25]
	s_nop 0
	v_cvt_pk_bf16_f32 v21, v22, v23
	global_store_dwordx4 v[52:53], v[18:21], off offset:64
	ds_read_b128 v[18:21], v1 offset:52224
	ds_read_b128 v[22:25], v1 offset:53312
	ds_read_b128 v[26:29], v1 offset:52288
	ds_read_b128 v[30:33], v1 offset:53376
	s_waitcnt lgkmcnt(3)
	v_mfma_f32_16x16x32_bf16 v[18:21], v[18:21], v[46:49], 0
	s_waitcnt lgkmcnt(2)
	v_mfma_f32_16x16x32_bf16 v[22:25], v[22:25], v[46:49], 0
	s_waitcnt lgkmcnt(1)
	v_mfma_f32_16x16x32_bf16 v[18:21], v[26:29], v[42:45], v[18:21]
	s_waitcnt lgkmcnt(0)
	v_mfma_f32_16x16x32_bf16 v[22:25], v[30:33], v[42:45], v[22:25]
	ds_read_b128 v[26:29], v1 offset:52352
	ds_read_b128 v[30:33], v1 offset:53440
	s_waitcnt lgkmcnt(1)
	v_mfma_f32_16x16x32_bf16 v[18:21], v[26:29], v[38:41], v[18:21]
	s_waitcnt lgkmcnt(0)
	v_mfma_f32_16x16x32_bf16 v[22:25], v[30:33], v[38:41], v[22:25]
	ds_read_b128 v[26:29], v1 offset:52416
	ds_read_b128 v[30:33], v1 offset:53504
	s_waitcnt lgkmcnt(1)
	v_mfma_f32_16x16x32_bf16 v[18:21], v[26:29], v[34:37], v[18:21]
	v_lshlrev_b32_e32 v26, 16, v14
	v_and_b32_e32 v27, 0xffff0000, v14
	v_lshlrev_b32_e32 v14, 16, v15
	s_waitcnt lgkmcnt(0)
	v_mfma_f32_16x16x32_bf16 v[22:25], v[30:33], v[34:37], v[22:25]
	s_nop 2
	v_add_f32_e64 v18, v50, v18
	v_add_f32_e64 v19, v50, v19
	v_pk_mul_f32 v[18:19], v[18:19], v[26:27]
	v_lshlrev_b32_e32 v26, 16, v10
	v_and_b32_e32 v27, 0xffff0000, v10
	v_pk_mul_f32 v[18:19], v[18:19], v[26:27]
	v_and_b32_e32 v15, 0xffff0000, v15
	v_cvt_pk_bf16_f32 v10, v18, v19
	v_pk_add_f32 v[18:19], v[50:51], v[20:21] op_sel_hi:[0,1]
	v_pk_mul_f32 v[14:15], v[18:19], v[14:15]
	v_lshlrev_b32_e32 v18, 16, v11
	v_and_b32_e32 v19, 0xffff0000, v11
	v_pk_mul_f32 v[14:15], v[14:15], v[18:19]
	v_pk_add_f32 v[18:19], v[50:51], v[22:23] op_sel_hi:[0,1]
	v_cvt_pk_bf16_f32 v11, v14, v15
	v_lshlrev_b32_e32 v14, 16, v16
	v_and_b32_e32 v15, 0xffff0000, v16
	v_pk_mul_f32 v[14:15], v[18:19], v[14:15]
	v_lshlrev_b32_e32 v18, 16, v12
	v_and_b32_e32 v19, 0xffff0000, v12
	v_pk_mul_f32 v[14:15], v[14:15], v[18:19]
	s_nop 0
	v_cvt_pk_bf16_f32 v12, v14, v15
	v_lshlrev_b32_e32 v14, 16, v17
	v_and_b32_e32 v15, 0xffff0000, v17
	v_pk_add_f32 v[16:17], v[50:51], v[24:25] op_sel_hi:[0,1]
	v_pk_mul_f32 v[14:15], v[16:17], v[14:15]
	v_lshlrev_b32_e32 v16, 16, v13
	v_and_b32_e32 v17, 0xffff0000, v13
	v_pk_mul_f32 v[14:15], v[14:15], v[16:17]
	s_nop 0
	v_cvt_pk_bf16_f32 v13, v14, v15
	global_store_dwordx4 v[52:53], v[10:13], off offset:128
	ds_read_b128 v[10:13], v1 offset:60928
	ds_read_b128 v[14:17], v1 offset:62016
	ds_read_b128 v[18:21], v1 offset:60992
	ds_read_b128 v[22:25], v1 offset:62080
	s_waitcnt lgkmcnt(3)
	v_mfma_f32_16x16x32_bf16 v[10:13], v[10:13], v[46:49], 0
	s_waitcnt lgkmcnt(2)
	v_mfma_f32_16x16x32_bf16 v[14:17], v[14:17], v[46:49], 0
	s_waitcnt lgkmcnt(1)
	v_mfma_f32_16x16x32_bf16 v[10:13], v[18:21], v[42:45], v[10:13]
	s_waitcnt lgkmcnt(0)
	v_mfma_f32_16x16x32_bf16 v[14:17], v[22:25], v[42:45], v[14:17]
	ds_read_b128 v[18:21], v1 offset:61056
	ds_read_b128 v[22:25], v1 offset:62144
	s_waitcnt lgkmcnt(1)
	v_mfma_f32_16x16x32_bf16 v[10:13], v[18:21], v[38:41], v[10:13]
	s_waitcnt lgkmcnt(0)
	v_mfma_f32_16x16x32_bf16 v[14:17], v[22:25], v[38:41], v[14:17]
	ds_read_b128 v[18:21], v1 offset:61120
	ds_read_b128 v[22:25], v1 offset:62208
	s_waitcnt lgkmcnt(1)
	v_mfma_f32_16x16x32_bf16 v[10:13], v[18:21], v[34:37], v[10:13]
	v_lshlrev_b32_e32 v18, 16, v6
	v_and_b32_e32 v19, 0xffff0000, v6
	v_lshlrev_b32_e32 v6, 16, v7
	s_waitcnt lgkmcnt(0)
	v_mfma_f32_16x16x32_bf16 v[14:17], v[22:25], v[34:37], v[14:17]
	s_nop 2
	v_add_f32_e64 v10, v50, v10
	v_add_f32_e64 v11, v50, v11
	v_pk_mul_f32 v[10:11], v[10:11], v[18:19]
	v_lshlrev_b32_e32 v18, 16, v2
	v_and_b32_e32 v19, 0xffff0000, v2
	v_pk_mul_f32 v[10:11], v[10:11], v[18:19]
	v_and_b32_e32 v7, 0xffff0000, v7
	v_cvt_pk_bf16_f32 v2, v10, v11
	v_pk_add_f32 v[10:11], v[50:51], v[12:13] op_sel_hi:[0,1]
	v_pk_mul_f32 v[6:7], v[10:11], v[6:7]
	v_lshlrev_b32_e32 v10, 16, v3
	v_and_b32_e32 v11, 0xffff0000, v3
	v_pk_mul_f32 v[6:7], v[6:7], v[10:11]
	v_pk_add_f32 v[10:11], v[50:51], v[14:15] op_sel_hi:[0,1]
	v_cvt_pk_bf16_f32 v3, v6, v7
	v_lshlrev_b32_e32 v6, 16, v8
	v_and_b32_e32 v7, 0xffff0000, v8
	v_pk_mul_f32 v[6:7], v[10:11], v[6:7]
	v_lshlrev_b32_e32 v10, 16, v4
	v_and_b32_e32 v11, 0xffff0000, v4
	v_pk_mul_f32 v[6:7], v[6:7], v[10:11]
	s_nop 0
	v_cvt_pk_bf16_f32 v4, v6, v7
	v_lshlrev_b32_e32 v6, 16, v9
	v_and_b32_e32 v7, 0xffff0000, v9
	v_pk_add_f32 v[8:9], v[50:51], v[16:17] op_sel_hi:[0,1]
	v_pk_mul_f32 v[6:7], v[8:9], v[6:7]
	v_lshlrev_b32_e32 v8, 16, v5
	v_and_b32_e32 v9, 0xffff0000, v5
	v_pk_mul_f32 v[6:7], v[6:7], v[8:9]
	s_nop 0
	v_cvt_pk_bf16_f32 v5, v6, v7
	global_store_dwordx4 v[52:53], v[2:5], off offset:192
	s_waitcnt lgkmcnt(0)
	s_barrier
	s_cbranch_scc1 .LBB0_762
